# per-layer Wdn weight conversion also moved into the gate/up tail round for idle WGs 128-255 (in-proj phases start directly with the GEMM), on top of conv move + scan K^T pair-writes
# speedup vs baseline: 1.0103x; 1.0103x over previous
; __device__ __forceinline__ const float* ka_in(kaptr p, int i) { return *(const float* const __attribute__((address_space(4)))*)(p + 8 * i); }
; __global__ void __launch_bounds__(NTHR, 2) fwd_mega(Args args_unused, int ph_lo, int ph_hi) {
;     ...
;         const int j = L >> 1; const bool isRet = (L & 1) == 0; const int pb = 1 + 6 * L; (void)j;
;         if (L > 0 && IN(pb)) { PH_BEGIN conv_plain(ka_in(ka, 11) + (size_t)L * FF * D, FF, D, (bf16*)(ws + WS_WDN), scr, gw, ngw, lane); __syncthreads(); }
.LBB0_121:
	s_mov_b32 s16, s18
	s_mul_i32 s0, s16, 6
	s_or_b32 s17, s0, 1
	s_cmp_gt_i32 s16, 0
	s_cselect_b64 s[4:5], -1, 0
	s_cmp_le_i32 s58, s17
	s_cselect_b64 s[6:7], -1, 0
	s_cmp_lt_i32 s17, s59
	s_cselect_b64 s[18:19], -1, 0
	s_and_b64 s[20:21], s[6:7], s[18:19]
	s_and_b64 s[4:5], s[4:5], s[20:21]
	s_andn2_b64 vcc, exec, s[4:5]
	s_branch .LBB0_132

; __device__ __forceinline__ const float* ka_in(kaptr p, int i) { return *(const float* const __attribute__((address_space(4)))*)(p + 8 * i); }
; __device__ __forceinline__ void tr_load(float (&v)[32], const TrItem& t, int lane) {
; #pragma unroll
;     for (int i = 0; i < 32; ++i) { const int kk = 2 * i + (lane >> 5); v[i] = t.W[(size_t)(t.k0 + kk) * t.Nsrc + t.c0 + (lane & 31)]; }
; }
; __global__ void __launch_bounds__(NTHR, 2) fwd_mega(Args args_unused, int ph_lo, int ph_hi) {
;     ...
;             if ((L + 1) & 1) { conv_plain(ka_in(ka, 4) + (size_t)nj * D * DIFF_IN, D, DIFF_IN, (bf16*)(ws + WS_WIN), scr, gw, ngw, lane); conv_plain(ka_in(ka, 5) + (size_t)nj * D * D, D, D, (bf16*)(ws + WS_WOUT), scr, gw, ngw, lane); }
;             else { conv_plain(ka_in(ka, 2) + (size_t)nj * D * RET_IN, D, RET_IN, (bf16*)(ws + WS_WIN), scr, gw, ngw, lane); conv_plain(ka_in(ka, 3) + (size_t)nj * 2048 * D, 2048, D, (bf16*)(ws + WS_WOUT), scr, gw, ngw, lane); }
;             conv_gu(ka_in(ka, 9) + (size_t)(L + 1) * D * FF, ka_in(ka, 10) + (size_t)(L + 1) * D * FF, (bf16*)(ws + WS_WGU), scr, gw, ngw, lane);
.LBB0_942:
	s_waitcnt vmcnt(0)
	v_readlane_b32 s56, v255, 4
	v_readlane_b32 s58, v255, 6
	v_readlane_b32 s52, v255, 8
	v_readlane_b32 s57, v255, 5
	v_readlane_b32 s59, v255, 7
	v_readlane_b32 s53, v255, 9
	v_readlane_b32 s55, v255, 10
	s_barrier
	v_readlane_b32 s5, v254, 0
	s_nop 3
	s_cmp_lt_u32 s5, 0x80
	s_cbranch_scc1 .Lcv_skip
	s_mov_b64 s[44:45], s[6:7]
	s_cmp_lt_i32 s16, 3
	s_cbranch_scc0 .Lcv_done
	s_add_i32 s18, s16, 1
	s_waitcnt lgkmcnt(0)
	s_mov_b64 s[26:27], s[56:57]
	s_waitcnt vmcnt(0)
	v_mov_b32_e32 v0, v228
	v_readlane_b32 s5, v254, 0
	s_load_dwordx2 s[24:25], s[26:27], 0x68
	s_lshl_b32 s5, s5, 3
	v_readfirstlane_b32 s4, v0
	s_ashr_i32 s4, s4, 6
	s_add_i32 s17, s5, s4
	s_addk_i32 s17, 0xfc00
	s_lshl_b32 s4, s4, 14
	v_bfe_u32 v33, v0, 5, 1
	v_and_b32_e32 v1, 31, v0
	v_bfe_u32 v45, v0, 3, 3
	v_lshlrev_b32_e32 v0, 3, v0
	s_add_i32 s4, s4, 0
	v_lshlrev_b32_e32 v34, 2, v1
	v_mul_u32_u24_e32 v1, 0x84, v33
	v_and_b32_e32 v50, 56, v0
	s_ashr_i32 s28, s18, 1
	v_add3_u32 v44, s4, v34, v1
	v_mul_u32_u24_e32 v0, 0x84, v50
	v_lshlrev_b32_e32 v1, 2, v45
	s_ashr_i32 s29, s28, 31
	v_add3_u32 v46, s4, v0, v1
	v_readlane_b32 s4, v255, 11
	s_waitcnt lgkmcnt(0)
	s_add_u32 s30, s24, 0x200000
	v_readlane_b32 s5, v255, 12
	s_addc_u32 s31, s25, 0
	v_or_b32_e32 v47, 8, v45
	v_or_b32_e32 v48, 16, v45
	v_or_b32_e32 v49, 24, v45
	s_mov_b64 s[6:7], -1
	s_and_b64 vcc, exec, s[4:5]
	s_cbranch_vccz .LcvA_b1032
	s_cmpk_gt_i32 s17, 0xbff
	s_cbranch_scc1 .LcvA_b1022
	s_load_dwordx2 s[4:5], s[26:27], 0x10
	s_mul_i32 s7, s28, 0x1800000
	s_mul_hi_i32 s6, s28, 0x1800000
	v_mov_b32_e32 v35, v32
	s_waitcnt lgkmcnt(0)
	s_add_u32 s4, s4, s7
	s_addc_u32 s5, s5, s6
	v_lshl_add_u64 v[36:37], s[4:5], 0, v[34:35]
	s_mul_hi_i32 s4, s17, 0x2aaaaaab
	s_lshr_b32 s5, s4, 31
	s_ashr_i32 s4, s4, 5
	s_add_i32 s5, s4, s5
	s_mul_i32 s4, s5, 0xc0
	s_sub_i32 s4, s17, s4
	s_lshl_b32 s4, s4, 5
	v_lshl_or_b32 v35, s5, 6, v33
	s_ashr_i32 s5, s4, 31
	v_lshl_add_u64 v[38:39], s[4:5], 2, v[36:37]
	v_mad_i64_i32 v[0:1], s[4:5], v35, s54, v[38:39]
	global_load_dword v0, v[0:1], off
	v_or_b32_e32 v1, 2, v35
	v_mad_i64_i32 v[2:3], s[4:5], v1, s54, v[38:39]
	global_load_dword v1, v[2:3], off
	v_or_b32_e32 v2, 4, v35
	v_mad_i64_i32 v[2:3], s[4:5], v2, s54, v[38:39]
	global_load_dword v2, v[2:3], off
	v_or_b32_e32 v3, 6, v35
	v_mad_i64_i32 v[4:5], s[4:5], v3, s54, v[38:39]
	global_load_dword v3, v[4:5], off
	v_or_b32_e32 v4, 8, v35
	v_mad_i64_i32 v[4:5], s[4:5], v4, s54, v[38:39]
	global_load_dword v4, v[4:5], off
	v_or_b32_e32 v5, 10, v35
	v_mad_i64_i32 v[6:7], s[4:5], v5, s54, v[38:39]
	global_load_dword v5, v[6:7], off
	v_or_b32_e32 v6, 12, v35
	v_mad_i64_i32 v[6:7], s[4:5], v6, s54, v[38:39]
	global_load_dword v6, v[6:7], off
	v_or_b32_e32 v7, 14, v35
	v_mad_i64_i32 v[8:9], s[4:5], v7, s54, v[38:39]
	global_load_dword v7, v[8:9], off
	v_or_b32_e32 v8, 16, v35
	v_mad_i64_i32 v[8:9], s[4:5], v8, s54, v[38:39]
	global_load_dword v8, v[8:9], off
	v_or_b32_e32 v9, 18, v35
	v_mad_i64_i32 v[10:11], s[4:5], v9, s54, v[38:39]
	global_load_dword v9, v[10:11], off
	v_or_b32_e32 v10, 20, v35
	v_mad_i64_i32 v[10:11], s[4:5], v10, s54, v[38:39]
	global_load_dword v10, v[10:11], off
	v_or_b32_e32 v11, 22, v35
	v_mad_i64_i32 v[12:13], s[4:5], v11, s54, v[38:39]
	global_load_dword v11, v[12:13], off
	v_or_b32_e32 v12, 24, v35
	v_mad_i64_i32 v[12:13], s[4:5], v12, s54, v[38:39]
	global_load_dword v12, v[12:13], off
	v_or_b32_e32 v13, 26, v35
	v_mad_i64_i32 v[14:15], s[4:5], v13, s54, v[38:39]
	global_load_dword v13, v[14:15], off
	v_or_b32_e32 v14, 28, v35
	v_mad_i64_i32 v[14:15], s[4:5], v14, s54, v[38:39]
	global_load_dword v14, v[14:15], off
	v_or_b32_e32 v15, 30, v35
	v_mad_i64_i32 v[16:17], s[4:5], v15, s54, v[38:39]
	global_load_dword v15, v[16:17], off
	v_or_b32_e32 v16, 32, v35
	v_mad_i64_i32 v[16:17], s[4:5], v16, s54, v[38:39]
	global_load_dword v16, v[16:17], off
	v_or_b32_e32 v17, 34, v35
	v_mad_i64_i32 v[18:19], s[4:5], v17, s54, v[38:39]
	global_load_dword v17, v[18:19], off
	v_or_b32_e32 v18, 36, v35
	v_mad_i64_i32 v[18:19], s[4:5], v18, s54, v[38:39]
	global_load_dword v18, v[18:19], off
	v_or_b32_e32 v19, 38, v35
	v_mad_i64_i32 v[20:21], s[4:5], v19, s54, v[38:39]
	global_load_dword v19, v[20:21], off
	v_or_b32_e32 v20, 40, v35
	v_mad_i64_i32 v[20:21], s[4:5], v20, s54, v[38:39]
	global_load_dword v20, v[20:21], off
	v_or_b32_e32 v21, 42, v35
	v_mad_i64_i32 v[22:23], s[4:5], v21, s54, v[38:39]
	global_load_dword v21, v[22:23], off
	v_or_b32_e32 v22, 44, v35
	v_mad_i64_i32 v[22:23], s[4:5], v22, s54, v[38:39]
	global_load_dword v22, v[22:23], off
	v_or_b32_e32 v23, 46, v35
	v_mad_i64_i32 v[24:25], s[4:5], v23, s54, v[38:39]
	global_load_dword v23, v[24:25], off
	v_or_b32_e32 v24, 48, v35
	v_mad_i64_i32 v[24:25], s[4:5], v24, s54, v[38:39]
	global_load_dword v24, v[24:25], off
	v_or_b32_e32 v25, 50, v35
	v_mad_i64_i32 v[26:27], s[4:5], v25, s54, v[38:39]
	global_load_dword v25, v[26:27], off
	v_or_b32_e32 v26, 52, v35
	v_mad_i64_i32 v[26:27], s[4:5], v26, s54, v[38:39]
	global_load_dword v26, v[26:27], off
	v_or_b32_e32 v27, 54, v35
	v_mad_i64_i32 v[28:29], s[4:5], v27, s54, v[38:39]
	global_load_dword v27, v[28:29], off
	v_or_b32_e32 v28, 56, v35
	v_mad_i64_i32 v[28:29], s[4:5], v28, s54, v[38:39]
	global_load_dword v28, v[28:29], off
	v_or_b32_e32 v29, 58, v35
	v_mad_i64_i32 v[30:31], s[4:5], v29, s54, v[38:39]
	global_load_dword v29, v[30:31], off
	v_or_b32_e32 v30, 60, v35
	v_mad_i64_i32 v[30:31], s[4:5], v30, s54, v[38:39]
	global_load_dword v30, v[30:31], off
	v_or_b32_e32 v31, 62, v35
	v_mad_i64_i32 v[38:39], s[4:5], v31, s54, v[38:39]
	global_load_dword v31, v[38:39], off
	v_lshlrev_b32_e32 v38, 1, v50
	s_mov_b32 s4, s17
	s_branch .LcvA_b1017

; __device__ __forceinline__ const float* ka_in(kaptr p, int i) { return *(const float* const __attribute__((address_space(4)))*)(p + 8 * i); }
; __global__ void __launch_bounds__(NTHR, 2) fwd_mega(Args args_unused, int ph_lo, int ph_hi) {
;     ...
;         if (L > 0 && IN(pb)) { PH_BEGIN conv_plain(ka_in(ka, 11) + (size_t)L * FF * D, FF, D, (bf16*)(ws + WS_WDN), scr, gw, ngw, lane); __syncthreads(); }
.Lcv_done:
	s_cmp_gt_i32 s16, 0
	s_cbranch_scc0 .Lwd_done
	s_mov_b64 s[6:7], s[56:57]
	s_waitcnt vmcnt(0)
	v_mov_b32_e32 v0, v228
	s_nop 0
	v_readfirstlane_b32 s4, v0
	s_ashr_i32 s5, s4, 6
	v_readlane_b32 s4, v254, 0
	s_lshl_b32 s4, s4, 3
	s_add_i32 s4, s4, s5
	s_addk_i32 s4, 0xfc00
	s_cmpk_gt_i32 s4, 0x57f
	s_cbranch_scc1 .Lwd_passA_done
; __device__ __forceinline__ void tr_load(float (&v)[32], const TrItem& t, int lane) {
; #pragma unroll
;     for (int i = 0; i < 32; ++i) { const int kk = 2 * i + (lane >> 5); v[i] = t.W[(size_t)(t.k0 + kk) * t.Nsrc + t.c0 + (lane & 31)]; }
; }
	s_load_dwordx2 s[18:19], s[6:7], 0x58
	s_nop 0
	s_load_dwordx2 s[6:7], s[6:7], 0x68
	s_lshl_b32 s5, s5, 14
	s_add_i32 s5, s5, 0
	s_mul_i32 s22, s16, 0xb00000
	s_mul_hi_u32 s17, s16, 0xb00000
	s_waitcnt lgkmcnt(0)
	s_add_u32 s18, s18, s22
	v_bfe_u32 v33, v0, 5, 1
	v_lshlrev_b32_e32 v1, 2, v0
	v_bfe_u32 v42, v0, 3, 3
	v_lshlrev_b32_e32 v0, 3, v0
	s_addc_u32 s19, s19, s17
	v_and_b32_e32 v36, 56, v0
	s_add_u32 s6, s6, 0x1d00000
	v_and_b32_e32 v2, 0x7c, v1
	v_mul_u32_u24_e32 v0, 0x84, v36
	v_lshlrev_b32_e32 v1, 2, v42
	s_addc_u32 s7, s7, 0
	v_add_u32_e32 v37, s5, v2
	v_add3_u32 v43, s5, v0, v1
	s_ashr_i32 s5, s4, 31
	s_lshr_b32 s5, s5, 27
	s_add_i32 s5, s4, s5
	s_and_b32 s17, s5, 0x7ffffe0
	s_lshl_b32 s5, s5, 1
	s_andn2_b32 s5, s5, 63
	v_mov_b32_e32 v3, v32
	s_sub_i32 s17, s4, s17
	v_or_b32_e32 v40, s5, v33
	v_lshl_add_u64 v[34:35], s[18:19], 0, v[2:3]
	s_lshl_b32 s18, s17, 5
	v_or_b32_e32 v2, 2, v40
	s_ashr_i32 s19, s18, 31
	v_ashrrev_i32_e32 v41, 31, v40
	v_ashrrev_i32_e32 v3, 31, v2
	v_lshl_add_u64 v[38:39], s[18:19], 2, v[34:35]
	v_lshlrev_b64 v[0:1], 12, v[40:41]
	v_lshlrev_b64 v[2:3], 12, v[2:3]
	v_lshl_add_u64 v[0:1], v[38:39], 0, v[0:1]
	v_lshl_add_u64 v[2:3], v[38:39], 0, v[2:3]
	global_load_dword v0, v[0:1], off
	v_or_b32_e32 v4, 6, v40
	global_load_dword v1, v[2:3], off
	v_or_b32_e32 v2, 4, v40
	v_ashrrev_i32_e32 v3, 31, v2
	v_ashrrev_i32_e32 v5, 31, v4
	v_lshlrev_b64 v[2:3], 12, v[2:3]
	v_lshlrev_b64 v[4:5], 12, v[4:5]
	v_lshl_add_u64 v[2:3], v[38:39], 0, v[2:3]
	v_lshl_add_u64 v[4:5], v[38:39], 0, v[4:5]
	global_load_dword v2, v[2:3], off
	v_or_b32_e32 v6, 10, v40
	global_load_dword v3, v[4:5], off
	v_or_b32_e32 v4, 8, v40
	v_ashrrev_i32_e32 v5, 31, v4
	v_ashrrev_i32_e32 v7, 31, v6
	v_lshlrev_b64 v[4:5], 12, v[4:5]
	v_lshlrev_b64 v[6:7], 12, v[6:7]
	v_lshl_add_u64 v[4:5], v[38:39], 0, v[4:5]
	v_lshl_add_u64 v[6:7], v[38:39], 0, v[6:7]
	global_load_dword v4, v[4:5], off
	v_or_b32_e32 v8, 14, v40
	global_load_dword v5, v[6:7], off
	v_or_b32_e32 v6, 12, v40
	v_ashrrev_i32_e32 v7, 31, v6
	v_ashrrev_i32_e32 v9, 31, v8
	v_lshlrev_b64 v[6:7], 12, v[6:7]
	v_lshlrev_b64 v[8:9], 12, v[8:9]
	v_lshl_add_u64 v[6:7], v[38:39], 0, v[6:7]
	v_lshl_add_u64 v[8:9], v[38:39], 0, v[8:9]
	global_load_dword v6, v[6:7], off
	v_or_b32_e32 v10, 18, v40
	global_load_dword v7, v[8:9], off
	v_or_b32_e32 v8, 16, v40
	v_ashrrev_i32_e32 v9, 31, v8
	v_ashrrev_i32_e32 v11, 31, v10
	v_lshlrev_b64 v[8:9], 12, v[8:9]
	v_lshlrev_b64 v[10:11], 12, v[10:11]
	v_lshl_add_u64 v[8:9], v[38:39], 0, v[8:9]
	v_lshl_add_u64 v[10:11], v[38:39], 0, v[10:11]
	global_load_dword v8, v[8:9], off
	v_or_b32_e32 v12, 22, v40
	global_load_dword v9, v[10:11], off
	v_or_b32_e32 v10, 20, v40
	v_ashrrev_i32_e32 v11, 31, v10
	v_ashrrev_i32_e32 v13, 31, v12
	v_lshlrev_b64 v[10:11], 12, v[10:11]
	v_lshlrev_b64 v[12:13], 12, v[12:13]
	v_lshl_add_u64 v[10:11], v[38:39], 0, v[10:11]
	v_lshl_add_u64 v[12:13], v[38:39], 0, v[12:13]
	global_load_dword v10, v[10:11], off
	v_or_b32_e32 v14, 26, v40
	global_load_dword v11, v[12:13], off
	v_or_b32_e32 v12, 24, v40
	v_ashrrev_i32_e32 v13, 31, v12
	v_ashrrev_i32_e32 v15, 31, v14
	v_lshlrev_b64 v[12:13], 12, v[12:13]
	v_lshlrev_b64 v[14:15], 12, v[14:15]
	v_lshl_add_u64 v[12:13], v[38:39], 0, v[12:13]
	v_lshl_add_u64 v[14:15], v[38:39], 0, v[14:15]
	global_load_dword v12, v[12:13], off
	v_or_b32_e32 v16, 30, v40
	global_load_dword v13, v[14:15], off
	v_or_b32_e32 v14, 28, v40
	v_ashrrev_i32_e32 v15, 31, v14
	v_ashrrev_i32_e32 v17, 31, v16
	v_lshlrev_b64 v[14:15], 12, v[14:15]
	v_lshlrev_b64 v[16:17], 12, v[16:17]
	v_lshl_add_u64 v[14:15], v[38:39], 0, v[14:15]
	v_lshl_add_u64 v[16:17], v[38:39], 0, v[16:17]
	global_load_dword v14, v[14:15], off
	v_or_b32_e32 v18, 34, v40
	global_load_dword v15, v[16:17], off
	v_or_b32_e32 v16, 32, v40
	v_ashrrev_i32_e32 v17, 31, v16
	v_ashrrev_i32_e32 v19, 31, v18
	v_lshlrev_b64 v[16:17], 12, v[16:17]
	v_lshlrev_b64 v[18:19], 12, v[18:19]
	v_lshl_add_u64 v[16:17], v[38:39], 0, v[16:17]
	v_lshl_add_u64 v[18:19], v[38:39], 0, v[18:19]
	global_load_dword v16, v[16:17], off
	v_or_b32_e32 v20, 38, v40
	global_load_dword v17, v[18:19], off
	v_or_b32_e32 v18, 36, v40
	v_ashrrev_i32_e32 v19, 31, v18
	v_ashrrev_i32_e32 v21, 31, v20
	v_lshlrev_b64 v[18:19], 12, v[18:19]
	v_lshlrev_b64 v[20:21], 12, v[20:21]
	v_lshl_add_u64 v[18:19], v[38:39], 0, v[18:19]
	v_lshl_add_u64 v[20:21], v[38:39], 0, v[20:21]
	global_load_dword v18, v[18:19], off
	v_or_b32_e32 v22, 42, v40
	global_load_dword v19, v[20:21], off
	v_or_b32_e32 v20, 40, v40
	v_ashrrev_i32_e32 v21, 31, v20
	v_ashrrev_i32_e32 v23, 31, v22
	v_lshlrev_b64 v[20:21], 12, v[20:21]
	v_lshlrev_b64 v[22:23], 12, v[22:23]
	v_lshl_add_u64 v[20:21], v[38:39], 0, v[20:21]
	v_lshl_add_u64 v[22:23], v[38:39], 0, v[22:23]
	global_load_dword v20, v[20:21], off
	v_or_b32_e32 v24, 46, v40
	global_load_dword v21, v[22:23], off
	v_or_b32_e32 v22, 44, v40
	v_ashrrev_i32_e32 v23, 31, v22
	v_ashrrev_i32_e32 v25, 31, v24
	v_lshlrev_b64 v[22:23], 12, v[22:23]
	v_lshlrev_b64 v[24:25], 12, v[24:25]
	v_lshl_add_u64 v[22:23], v[38:39], 0, v[22:23]
	v_lshl_add_u64 v[24:25], v[38:39], 0, v[24:25]
	global_load_dword v22, v[22:23], off
	v_or_b32_e32 v26, 50, v40
	global_load_dword v23, v[24:25], off
	v_or_b32_e32 v24, 48, v40
	v_ashrrev_i32_e32 v25, 31, v24
	v_ashrrev_i32_e32 v27, 31, v26
	v_lshlrev_b64 v[24:25], 12, v[24:25]
	v_lshlrev_b64 v[26:27], 12, v[26:27]
	v_lshl_add_u64 v[24:25], v[38:39], 0, v[24:25]
	v_lshl_add_u64 v[26:27], v[38:39], 0, v[26:27]
	global_load_dword v24, v[24:25], off
	v_or_b32_e32 v28, 54, v40
	global_load_dword v25, v[26:27], off
	v_or_b32_e32 v26, 52, v40
	v_ashrrev_i32_e32 v27, 31, v26
	v_ashrrev_i32_e32 v29, 31, v28
	v_lshlrev_b64 v[26:27], 12, v[26:27]
	v_lshlrev_b64 v[28:29], 12, v[28:29]
	v_lshl_add_u64 v[26:27], v[38:39], 0, v[26:27]
	v_lshl_add_u64 v[28:29], v[38:39], 0, v[28:29]
	global_load_dword v26, v[26:27], off
	v_or_b32_e32 v30, 58, v40
	global_load_dword v27, v[28:29], off
	v_or_b32_e32 v28, 56, v40
	v_ashrrev_i32_e32 v29, 31, v28
	s_waitcnt vmcnt(32)
	v_ashrrev_i32_e32 v31, 31, v30
	v_lshlrev_b64 v[28:29], 12, v[28:29]
	v_lshlrev_b64 v[30:31], 12, v[30:31]
	v_lshl_add_u64 v[28:29], v[38:39], 0, v[28:29]
	v_lshl_add_u64 v[30:31], v[38:39], 0, v[30:31]
	global_load_dword v28, v[28:29], off
	v_mul_u32_u24_e32 v47, 0x84, v33
	global_load_dword v29, v[30:31], off
	v_or_b32_e32 v30, 60, v40
	v_or_b32_e32 v40, 62, v40
	v_ashrrev_i32_e32 v31, 31, v30
	v_ashrrev_i32_e32 v41, 31, v40
	v_lshlrev_b64 v[30:31], 12, v[30:31]
	v_lshlrev_b64 v[40:41], 12, v[40:41]
	v_lshl_add_u64 v[30:31], v[38:39], 0, v[30:31]
	v_lshl_add_u64 v[38:39], v[38:39], 0, v[40:41]
	global_load_dword v30, v[30:31], off
	v_or_b32_e32 v44, 8, v42
	global_load_dword v31, v[38:39], off
	v_or_b32_e32 v45, 16, v42
	v_or_b32_e32 v46, 24, v42
	v_lshlrev_b32_e32 v36, 1, v36
	v_add_u32_e32 v38, v37, v47
	s_branch .LwdA_b126

; __device__ __forceinline__ const float* ka_in(kaptr p, int i) { return *(const float* const __attribute__((address_space(4)))*)(p + 8 * i); }
; __global__ void __launch_bounds__(NTHR, 2) fwd_mega(Args args_unused, int ph_lo, int ph_hi) {
;     ...
;         if (L > 0 && IN(pb)) { PH_BEGIN conv_plain(ka_in(ka, 11) + (size_t)L * FF * D, FF, D, (bf16*)(ws + WS_WDN), scr, gw, ngw, lane); __syncthreads(); }
.Lwd_passA_done:
	s_mov_b64 s[6:7], s[56:57]
	s_waitcnt vmcnt(0)
	v_mov_b32_e32 v0, v228
	s_nop 0
	v_readfirstlane_b32 s4, v0
	s_ashr_i32 s5, s4, 6
	v_readlane_b32 s4, v254, 0
	s_lshl_b32 s4, s4, 3
	s_add_i32 s4, s4, s5
	s_cmpk_gt_i32 s4, 0x57f
	s_cbranch_scc1 .Lwd_done
; __device__ __forceinline__ void tr_load(float (&v)[32], const TrItem& t, int lane) {
; #pragma unroll
;     for (int i = 0; i < 32; ++i) { const int kk = 2 * i + (lane >> 5); v[i] = t.W[(size_t)(t.k0 + kk) * t.Nsrc + t.c0 + (lane & 31)]; }
; }
	s_load_dwordx2 s[18:19], s[6:7], 0x58
	s_nop 0
	s_load_dwordx2 s[6:7], s[6:7], 0x68
	s_lshl_b32 s5, s5, 14
	s_add_i32 s5, s5, 0
	s_mul_i32 s22, s16, 0xb00000
	s_mul_hi_u32 s17, s16, 0xb00000
	s_waitcnt lgkmcnt(0)
	s_add_u32 s18, s18, s22
	v_bfe_u32 v33, v0, 5, 1
	v_lshlrev_b32_e32 v1, 2, v0
	v_bfe_u32 v42, v0, 3, 3
	v_lshlrev_b32_e32 v0, 3, v0
	s_addc_u32 s19, s19, s17
	v_and_b32_e32 v36, 56, v0
	s_add_u32 s6, s6, 0x1d00000
	v_and_b32_e32 v2, 0x7c, v1
	v_mul_u32_u24_e32 v0, 0x84, v36
	v_lshlrev_b32_e32 v1, 2, v42
	s_addc_u32 s7, s7, 0
	v_add_u32_e32 v37, s5, v2
	v_add3_u32 v43, s5, v0, v1
	s_ashr_i32 s5, s4, 31
	s_lshr_b32 s5, s5, 27
	s_add_i32 s5, s4, s5
	s_and_b32 s17, s5, 0x7ffffe0
	s_lshl_b32 s5, s5, 1
	s_andn2_b32 s5, s5, 63
	v_mov_b32_e32 v3, v32
	s_sub_i32 s17, s4, s17
	v_or_b32_e32 v40, s5, v33
	v_lshl_add_u64 v[34:35], s[18:19], 0, v[2:3]
	s_lshl_b32 s18, s17, 5
	v_or_b32_e32 v2, 2, v40
	s_ashr_i32 s19, s18, 31
	v_ashrrev_i32_e32 v41, 31, v40
	v_ashrrev_i32_e32 v3, 31, v2
	v_lshl_add_u64 v[38:39], s[18:19], 2, v[34:35]
	v_lshlrev_b64 v[0:1], 12, v[40:41]
	v_lshlrev_b64 v[2:3], 12, v[2:3]
	v_lshl_add_u64 v[0:1], v[38:39], 0, v[0:1]
	v_lshl_add_u64 v[2:3], v[38:39], 0, v[2:3]
	global_load_dword v0, v[0:1], off
	v_or_b32_e32 v4, 6, v40
	global_load_dword v1, v[2:3], off
	v_or_b32_e32 v2, 4, v40
	v_ashrrev_i32_e32 v3, 31, v2
	v_ashrrev_i32_e32 v5, 31, v4
	v_lshlrev_b64 v[2:3], 12, v[2:3]
	v_lshlrev_b64 v[4:5], 12, v[4:5]
	v_lshl_add_u64 v[2:3], v[38:39], 0, v[2:3]
	v_lshl_add_u64 v[4:5], v[38:39], 0, v[4:5]
	global_load_dword v2, v[2:3], off
	v_or_b32_e32 v6, 10, v40
	global_load_dword v3, v[4:5], off
	v_or_b32_e32 v4, 8, v40
	v_ashrrev_i32_e32 v5, 31, v4
	v_ashrrev_i32_e32 v7, 31, v6
	v_lshlrev_b64 v[4:5], 12, v[4:5]
	v_lshlrev_b64 v[6:7], 12, v[6:7]
	v_lshl_add_u64 v[4:5], v[38:39], 0, v[4:5]
	v_lshl_add_u64 v[6:7], v[38:39], 0, v[6:7]
	global_load_dword v4, v[4:5], off
	v_or_b32_e32 v8, 14, v40
	global_load_dword v5, v[6:7], off
	v_or_b32_e32 v6, 12, v40
	v_ashrrev_i32_e32 v7, 31, v6
	v_ashrrev_i32_e32 v9, 31, v8
	v_lshlrev_b64 v[6:7], 12, v[6:7]
	v_lshlrev_b64 v[8:9], 12, v[8:9]
	v_lshl_add_u64 v[6:7], v[38:39], 0, v[6:7]
	v_lshl_add_u64 v[8:9], v[38:39], 0, v[8:9]
	global_load_dword v6, v[6:7], off
	v_or_b32_e32 v10, 18, v40
	global_load_dword v7, v[8:9], off
	v_or_b32_e32 v8, 16, v40
	v_ashrrev_i32_e32 v9, 31, v8
	v_ashrrev_i32_e32 v11, 31, v10
	v_lshlrev_b64 v[8:9], 12, v[8:9]
	v_lshlrev_b64 v[10:11], 12, v[10:11]
	v_lshl_add_u64 v[8:9], v[38:39], 0, v[8:9]
	v_lshl_add_u64 v[10:11], v[38:39], 0, v[10:11]
	global_load_dword v8, v[8:9], off
	v_or_b32_e32 v12, 22, v40
	global_load_dword v9, v[10:11], off
	v_or_b32_e32 v10, 20, v40
	v_ashrrev_i32_e32 v11, 31, v10
	v_ashrrev_i32_e32 v13, 31, v12
	v_lshlrev_b64 v[10:11], 12, v[10:11]
	v_lshlrev_b64 v[12:13], 12, v[12:13]
	v_lshl_add_u64 v[10:11], v[38:39], 0, v[10:11]
	v_lshl_add_u64 v[12:13], v[38:39], 0, v[12:13]
	global_load_dword v10, v[10:11], off
	v_or_b32_e32 v14, 26, v40
	global_load_dword v11, v[12:13], off
	v_or_b32_e32 v12, 24, v40
	v_ashrrev_i32_e32 v13, 31, v12
	v_ashrrev_i32_e32 v15, 31, v14
	v_lshlrev_b64 v[12:13], 12, v[12:13]
	v_lshlrev_b64 v[14:15], 12, v[14:15]
	v_lshl_add_u64 v[12:13], v[38:39], 0, v[12:13]
	v_lshl_add_u64 v[14:15], v[38:39], 0, v[14:15]
	global_load_dword v12, v[12:13], off
	v_or_b32_e32 v16, 30, v40
	global_load_dword v13, v[14:15], off
	v_or_b32_e32 v14, 28, v40
	v_ashrrev_i32_e32 v15, 31, v14
	v_ashrrev_i32_e32 v17, 31, v16
	v_lshlrev_b64 v[14:15], 12, v[14:15]
	v_lshlrev_b64 v[16:17], 12, v[16:17]
	v_lshl_add_u64 v[14:15], v[38:39], 0, v[14:15]
	v_lshl_add_u64 v[16:17], v[38:39], 0, v[16:17]
	global_load_dword v14, v[14:15], off
	v_or_b32_e32 v18, 34, v40
	global_load_dword v15, v[16:17], off
	v_or_b32_e32 v16, 32, v40
	v_ashrrev_i32_e32 v17, 31, v16
	v_ashrrev_i32_e32 v19, 31, v18
	v_lshlrev_b64 v[16:17], 12, v[16:17]
	v_lshlrev_b64 v[18:19], 12, v[18:19]
	v_lshl_add_u64 v[16:17], v[38:39], 0, v[16:17]
	v_lshl_add_u64 v[18:19], v[38:39], 0, v[18:19]
	global_load_dword v16, v[16:17], off
	v_or_b32_e32 v20, 38, v40
	global_load_dword v17, v[18:19], off
	v_or_b32_e32 v18, 36, v40
	v_ashrrev_i32_e32 v19, 31, v18
	v_ashrrev_i32_e32 v21, 31, v20
	v_lshlrev_b64 v[18:19], 12, v[18:19]
	v_lshlrev_b64 v[20:21], 12, v[20:21]
	v_lshl_add_u64 v[18:19], v[38:39], 0, v[18:19]
	v_lshl_add_u64 v[20:21], v[38:39], 0, v[20:21]
	global_load_dword v18, v[18:19], off
	v_or_b32_e32 v22, 42, v40
	global_load_dword v19, v[20:21], off
	v_or_b32_e32 v20, 40, v40
	v_ashrrev_i32_e32 v21, 31, v20
	v_ashrrev_i32_e32 v23, 31, v22
	v_lshlrev_b64 v[20:21], 12, v[20:21]
	v_lshlrev_b64 v[22:23], 12, v[22:23]
	v_lshl_add_u64 v[20:21], v[38:39], 0, v[20:21]
	v_lshl_add_u64 v[22:23], v[38:39], 0, v[22:23]
	global_load_dword v20, v[20:21], off
	v_or_b32_e32 v24, 46, v40
	global_load_dword v21, v[22:23], off
	v_or_b32_e32 v22, 44, v40
	v_ashrrev_i32_e32 v23, 31, v22
	v_ashrrev_i32_e32 v25, 31, v24
	v_lshlrev_b64 v[22:23], 12, v[22:23]
	v_lshlrev_b64 v[24:25], 12, v[24:25]
	v_lshl_add_u64 v[22:23], v[38:39], 0, v[22:23]
	v_lshl_add_u64 v[24:25], v[38:39], 0, v[24:25]
	global_load_dword v22, v[22:23], off
	v_or_b32_e32 v26, 50, v40
	global_load_dword v23, v[24:25], off
	v_or_b32_e32 v24, 48, v40
	v_ashrrev_i32_e32 v25, 31, v24
	v_ashrrev_i32_e32 v27, 31, v26
	v_lshlrev_b64 v[24:25], 12, v[24:25]
	v_lshlrev_b64 v[26:27], 12, v[26:27]
	v_lshl_add_u64 v[24:25], v[38:39], 0, v[24:25]
	v_lshl_add_u64 v[26:27], v[38:39], 0, v[26:27]
	global_load_dword v24, v[24:25], off
	v_or_b32_e32 v28, 54, v40
	global_load_dword v25, v[26:27], off
	v_or_b32_e32 v26, 52, v40
	v_ashrrev_i32_e32 v27, 31, v26
	v_ashrrev_i32_e32 v29, 31, v28
	v_lshlrev_b64 v[26:27], 12, v[26:27]
	v_lshlrev_b64 v[28:29], 12, v[28:29]
	v_lshl_add_u64 v[26:27], v[38:39], 0, v[26:27]
	v_lshl_add_u64 v[28:29], v[38:39], 0, v[28:29]
	global_load_dword v26, v[26:27], off
	v_or_b32_e32 v30, 58, v40
	global_load_dword v27, v[28:29], off
	v_or_b32_e32 v28, 56, v40
	v_ashrrev_i32_e32 v29, 31, v28
	s_waitcnt vmcnt(32)
	v_ashrrev_i32_e32 v31, 31, v30
	v_lshlrev_b64 v[28:29], 12, v[28:29]
	v_lshlrev_b64 v[30:31], 12, v[30:31]
	v_lshl_add_u64 v[28:29], v[38:39], 0, v[28:29]
	v_lshl_add_u64 v[30:31], v[38:39], 0, v[30:31]
	global_load_dword v28, v[28:29], off
	v_mul_u32_u24_e32 v47, 0x84, v33
	global_load_dword v29, v[30:31], off
	v_or_b32_e32 v30, 60, v40
	v_or_b32_e32 v40, 62, v40
	v_ashrrev_i32_e32 v31, 31, v30
	v_ashrrev_i32_e32 v41, 31, v40
	v_lshlrev_b64 v[30:31], 12, v[30:31]
	v_lshlrev_b64 v[40:41], 12, v[40:41]
	v_lshl_add_u64 v[30:31], v[38:39], 0, v[30:31]
	v_lshl_add_u64 v[38:39], v[38:39], 0, v[40:41]
	global_load_dword v30, v[30:31], off
	v_or_b32_e32 v44, 8, v42
	global_load_dword v31, v[38:39], off
	v_or_b32_e32 v45, 16, v42
	v_or_b32_e32 v46, 24, v42
	v_lshlrev_b32_e32 v36, 1, v36
	v_add_u32_e32 v38, v37, v47
	s_branch .LwdB_b126

; #define LAS __attribute__((address_space(3)))
; __device__ __forceinline__ unsigned pk2(float lo, float hi) { return (unsigned)f2bf1(lo) | ((unsigned)f2bf1(hi) << 16); }
; __device__ __forceinline__ void tr_finish(const float (&v)[32], const TrItem& t, bf16* WT, LAS float* scr, int lane) {
; #pragma unroll
;     for (int i = 0; i < 32; ++i) { const int kk = 2 * i + (lane >> 5); scr[kk * 33 + (lane & 31)] = v[i]; }
;     asm volatile("s_waitcnt lgkmcnt(0)" ::: "memory");
;     const int c = lane & 7;
; #pragma unroll
;     for (int j = 0; j < 4; ++j) { const int n = (lane >> 3) + 8 * j; const LAS float* s = scr + (8 * c) * 33 + n;
;         v4u o; o.x = pk2(s[0 * 33], s[1 * 33]); o.y = pk2(s[2 * 33], s[3 * 33]); o.z = pk2(s[4 * 33], s[5 * 33]); o.w = pk2(s[6 * 33], s[7 * 33]);
;         *(v4u*)(WT + (size_t)(t.r0 + n) * t.K + t.k0 + 8 * c) = o; }
;     asm volatile("s_waitcnt lgkmcnt(0)" ::: "memory");
; }
.LwdB_b128:
	v_add_u32_e32 v76, 0x400, v38
	v_add_u32_e32 v77, 0x800, v38
	v_add_u32_e32 v78, 0xc00, v38
	v_add_u32_e32 v79, 0x1000, v38
	v_add_u32_e32 v80, 0x1400, v38
	v_add_u32_e32 v81, 0x1800, v38
	v_add_u32_e32 v82, 0x1c00, v38
	s_waitcnt vmcnt(30)
	ds_write2_b32 v38, v0, v1 offset1:66
	s_waitcnt vmcnt(28)
	ds_write2_b32 v38, v2, v3 offset0:132 offset1:198
	s_waitcnt vmcnt(26)
	ds_write2_b32 v76, v4, v5 offset0:8 offset1:74
	s_waitcnt vmcnt(24)
	ds_write2_b32 v76, v6, v7 offset0:140 offset1:206
	s_waitcnt vmcnt(22)
	ds_write2_b32 v77, v8, v9 offset0:16 offset1:82
	s_waitcnt vmcnt(20)
	ds_write2_b32 v77, v10, v11 offset0:148 offset1:214
	s_waitcnt vmcnt(18)
	ds_write2_b32 v78, v12, v13 offset0:24 offset1:90
	s_waitcnt vmcnt(16)
	ds_write2_b32 v78, v14, v15 offset0:156 offset1:222
	s_waitcnt vmcnt(14)
	ds_write2_b32 v79, v16, v17 offset0:32 offset1:98
	s_waitcnt vmcnt(12)
	ds_write2_b32 v79, v18, v19 offset0:164 offset1:230
	s_waitcnt vmcnt(10)
	ds_write2_b32 v80, v20, v21 offset0:40 offset1:106
	s_waitcnt vmcnt(8)
	ds_write2_b32 v80, v22, v23 offset0:172 offset1:238
	s_waitcnt vmcnt(6)
	ds_write2_b32 v81, v24, v25 offset0:48 offset1:114
	s_waitcnt vmcnt(4)
	ds_write2_b32 v81, v26, v27 offset0:180 offset1:246
	s_waitcnt vmcnt(2)
	ds_write2_b32 v82, v28, v29 offset0:56 offset1:122
	s_waitcnt vmcnt(0)
	ds_write2_b32 v82, v30, v31 offset0:188 offset1:254
	s_waitcnt lgkmcnt(0)
	ds_read2_b32 v[88:89], v43 offset1:8
	ds_read2_b32 v[92:93], v43 offset0:66 offset1:74
	ds_read2_b32 v[90:91], v43 offset0:33 offset1:41
	ds_read2_b32 v[94:95], v43 offset0:99 offset1:107
	ds_read2_b32 v[96:97], v43 offset0:132 offset1:140
	ds_read2_b32 v[98:99], v43 offset0:165 offset1:173
	s_waitcnt lgkmcnt(5)
	v_bfe_u32 v37, v88, 16, 1
	s_waitcnt lgkmcnt(4)
	v_bfe_u32 v84, v92, 16, 1
	v_add3_u32 v37, v88, v37, s39
	s_waitcnt lgkmcnt(3)
	v_bfe_u32 v83, v90, 16, 1
	v_add3_u32 v84, v92, v84, s39
	ds_read2_b32 v[100:101], v43 offset0:198 offset1:206
	v_lshrrev_b32_e32 v37, 16, v37
	v_add3_u32 v83, v90, v83, s39
	v_lshrrev_b32_e32 v85, 16, v84
	s_waitcnt lgkmcnt(3)
	v_bfe_u32 v84, v94, 16, 1
	ds_read2_b32 v[102:103], v43 offset0:231 offset1:239
	v_add3_u32 v86, v94, v84, s39
	v_and_or_b32 v84, v83, s96, v37
	s_waitcnt lgkmcnt(3)
	v_bfe_u32 v37, v96, 16, 1
	s_ashr_i32 s17, s4, 31
	v_add3_u32 v37, v96, v37, s39
	s_waitcnt lgkmcnt(2)
	v_bfe_u32 v83, v98, 16, 1
	s_lshr_b32 s17, s17, 27
	v_lshrrev_b32_e32 v37, 16, v37
	v_add3_u32 v83, v98, v83, s39
	s_add_i32 s17, s4, s17
	v_and_or_b32 v85, v86, s96, v85
	v_and_or_b32 v86, v83, s96, v37
	s_waitcnt lgkmcnt(1)
	v_bfe_u32 v37, v100, 16, 1
	s_and_b32 s22, s17, 0x7ffffe0
	v_add3_u32 v37, v100, v37, s39
	s_waitcnt lgkmcnt(0)
	v_bfe_u32 v83, v102, 16, 1
	s_sub_i32 s23, s4, s22
	s_lshl_b32 s17, s17, 1
	v_lshrrev_b32_e32 v37, 16, v37
	v_add3_u32 v83, v102, v83, s39
	s_and_b32 s22, s17, 0xffffffc0
	s_lshl_b32 s17, s23, 5
	v_and_or_b32 v87, v83, s96, v37
	v_or_b32_e32 v37, s17, v42
	v_mul_lo_u32 v104, v37, s97
	v_ashrrev_i32_e32 v105, 31, v104
	s_ashr_i32 s23, s22, 31
	v_lshl_add_u64 v[104:105], v[104:105], 1, s[6:7]
	s_lshl_b64 s[22:23], s[22:23], 1
	v_lshl_add_u64 v[104:105], v[104:105], 0, s[22:23]
	v_mov_b32_e32 v37, v32
	v_lshl_add_u64 v[104:105], v[104:105], 0, v[36:37]
	v_bfe_u32 v83, v89, 16, 1
	global_store_dwordx4 v[104:105], v[84:87], off
	v_add3_u32 v83, v89, v83, s39
	v_lshrrev_b32_e32 v83, 16, v83
	v_bfe_u32 v84, v91, 16, 1
	v_bfe_u32 v85, v93, 16, 1
	v_add3_u32 v84, v91, v84, s39
	v_add3_u32 v85, v93, v85, s39
	v_bfe_u32 v86, v95, 16, 1
	v_add3_u32 v86, v95, v86, s39
	v_lshrrev_b32_e32 v85, 16, v85
	v_and_or_b32 v84, v84, s96, v83
	v_bfe_u32 v83, v97, 16, 1
	v_and_or_b32 v85, v86, s96, v85
	v_add3_u32 v83, v97, v83, s39
	v_bfe_u32 v86, v99, 16, 1
	v_add3_u32 v86, v99, v86, s39
	v_lshrrev_b32_e32 v83, 16, v83
	v_and_or_b32 v86, v86, s96, v83
	v_bfe_u32 v83, v101, 16, 1
	v_add3_u32 v83, v101, v83, s39
	v_bfe_u32 v87, v103, 16, 1
	v_add3_u32 v87, v103, v87, s39
	v_lshrrev_b32_e32 v83, 16, v83
	v_and_or_b32 v87, v87, s96, v83
	v_or_b32_e32 v83, s17, v44
	v_mul_lo_u32 v88, v83, s97
	v_ashrrev_i32_e32 v89, 31, v88
	v_lshl_add_u64 v[88:89], v[88:89], 1, s[6:7]
	v_lshl_add_u64 v[88:89], v[88:89], 0, s[22:23]
	v_lshl_add_u64 v[88:89], v[88:89], 0, v[36:37]
	global_store_dwordx4 v[88:89], v[84:87], off
	ds_read2_b32 v[88:89], v43 offset0:16 offset1:24
	ds_read2_b32 v[90:91], v43 offset0:49 offset1:57
	ds_read2_b32 v[92:93], v43 offset0:82 offset1:90
	ds_read2_b32 v[94:95], v43 offset0:115 offset1:123
	ds_read2_b32 v[96:97], v43 offset0:148 offset1:156
	ds_read2_b32 v[98:99], v43 offset0:181 offset1:189
	s_waitcnt lgkmcnt(5)
	v_bfe_u32 v83, v88, 16, 1
	v_add3_u32 v83, v88, v83, s39
	s_waitcnt lgkmcnt(4)
	v_bfe_u32 v84, v90, 16, 1
	s_waitcnt lgkmcnt(3)
	v_bfe_u32 v85, v92, 16, 1
	ds_read2_b32 v[100:101], v43 offset0:214 offset1:222
	v_lshrrev_b32_e32 v83, 16, v83
	v_add3_u32 v84, v90, v84, s39
	v_add3_u32 v85, v92, v85, s39
	s_waitcnt lgkmcnt(3)
	v_bfe_u32 v86, v94, 16, 1
	ds_read2_b32 v[102:103], v43 offset0:247 offset1:255
	v_lshrrev_b32_e32 v85, 16, v85
	v_add3_u32 v86, v94, v86, s39
	v_and_or_b32 v84, v84, s96, v83
	s_waitcnt lgkmcnt(3)
	v_bfe_u32 v83, v96, 16, 1
	v_and_or_b32 v85, v86, s96, v85
	v_add3_u32 v83, v96, v83, s39
	s_waitcnt lgkmcnt(2)
	v_bfe_u32 v86, v98, 16, 1
	v_lshrrev_b32_e32 v83, 16, v83
	v_add3_u32 v86, v98, v86, s39
	v_and_or_b32 v86, v86, s96, v83
	s_waitcnt lgkmcnt(1)
	v_bfe_u32 v83, v100, 16, 1
	v_add3_u32 v83, v100, v83, s39
	s_waitcnt lgkmcnt(0)
	v_bfe_u32 v87, v102, 16, 1
	v_lshrrev_b32_e32 v83, 16, v83
	v_add3_u32 v87, v102, v87, s39
	v_and_or_b32 v87, v87, s96, v83
	v_or_b32_e32 v83, s17, v45
	v_mul_lo_u32 v104, v83, s97
	v_ashrrev_i32_e32 v105, 31, v104
	v_lshl_add_u64 v[104:105], v[104:105], 1, s[6:7]
	v_lshl_add_u64 v[104:105], v[104:105], 0, s[22:23]
	v_lshl_add_u64 v[104:105], v[104:105], 0, v[36:37]
	v_bfe_u32 v83, v89, 16, 1
	global_store_dwordx4 v[104:105], v[84:87], off
	v_add3_u32 v83, v89, v83, s39
	v_lshrrev_b32_e32 v83, 16, v83
	v_bfe_u32 v84, v91, 16, 1
	v_bfe_u32 v85, v93, 16, 1
	v_add3_u32 v84, v91, v84, s39
	v_add3_u32 v85, v93, v85, s39
	v_bfe_u32 v86, v95, 16, 1
	v_add3_u32 v86, v95, v86, s39
	v_lshrrev_b32_e32 v85, 16, v85
	v_and_or_b32 v84, v84, s96, v83
	v_bfe_u32 v83, v97, 16, 1
	v_and_or_b32 v85, v86, s96, v85
	v_add3_u32 v83, v97, v83, s39
	v_bfe_u32 v86, v99, 16, 1
	v_add3_u32 v86, v99, v86, s39
	v_lshrrev_b32_e32 v83, 16, v83
	v_and_or_b32 v86, v86, s96, v83
	v_bfe_u32 v83, v101, 16, 1
	v_add3_u32 v83, v101, v83, s39
	v_bfe_u32 v87, v103, 16, 1
	v_add3_u32 v87, v103, v87, s39
	v_lshrrev_b32_e32 v83, 16, v83
	v_and_or_b32 v87, v87, s96, v83
	v_or_b32_e32 v83, s17, v46
	v_mul_lo_u32 v88, v83, s97
	v_ashrrev_i32_e32 v89, 31, v88
	v_lshl_add_u64 v[88:89], v[88:89], 1, s[6:7]
	v_lshl_add_u64 v[88:89], v[88:89], 0, s[22:23]
	v_lshl_add_u64 v[88:89], v[88:89], 0, v[36:37]
	global_store_dwordx4 v[88:89], v[84:87], off
	s_waitcnt lgkmcnt(0)
	s_andn2_b64 vcc, exec, s[18:19]
	s_mov_b64 s[18:19], -1
	s_cbranch_vccnz .LwdB_b125
; #define LAS __attribute__((address_space(3)))
; __device__ __forceinline__ unsigned pk2(float lo, float hi) { return (unsigned)f2bf1(lo) | ((unsigned)f2bf1(hi) << 16); }
; __device__ __forceinline__ const float* ka_in(kaptr p, int i) { return *(const float* const __attribute__((address_space(4)))*)(p + 8 * i); }
; __device__ __forceinline__ void tr_load(float (&v)[32], const TrItem& t, int lane) {
; #pragma unroll
;     for (int i = 0; i < 32; ++i) { const int kk = 2 * i + (lane >> 5); v[i] = t.W[(size_t)(t.k0 + kk) * t.Nsrc + t.c0 + (lane & 31)]; }
; }
; __device__ __forceinline__ void tr_finish(const float (&v)[32], const TrItem& t, bf16* WT, LAS float* scr, int lane) {
; #pragma unroll
;     for (int i = 0; i < 32; ++i) { const int kk = 2 * i + (lane >> 5); scr[kk * 33 + (lane & 31)] = v[i]; }
;     asm volatile("s_waitcnt lgkmcnt(0)" ::: "memory");
;     const int c = lane & 7;
; #pragma unroll
;     for (int j = 0; j < 4; ++j) { const int n = (lane >> 3) + 8 * j; const LAS float* s = scr + (8 * c) * 33 + n;
;         v4u o; o.x = pk2(s[0 * 33], s[1 * 33]); o.y = pk2(s[2 * 33], s[3 * 33]); o.z = pk2(s[4 * 33], s[5 * 33]); o.w = pk2(s[6 * 33], s[7 * 33]);
;         *(v4u*)(WT + (size_t)(t.r0 + n) * t.K + t.k0 + 8 * c) = o; }
;     asm volatile("s_waitcnt lgkmcnt(0)" ::: "memory");
; }
; __global__ void __launch_bounds__(NTHR, 2) fwd_mega(Args args_unused, int ph_lo, int ph_hi) {
;     ...
;         if (L > 0 && IN(pb)) { PH_BEGIN conv_plain(ka_in(ka, 11) + (size_t)L * FF * D, FF, D, (bf16*)(ws + WS_WDN), scr, gw, ngw, lane); __syncthreads(); }
	s_add_i32 s4, s38, s4
	s_cmpk_gt_i32 s4, 0x57f
	s_cbranch_scc1 .LwdB_b124
	s_ashr_i32 s17, s4, 31
	s_lshr_b32 s17, s17, 27
	s_add_i32 s17, s4, s17
	s_and_b32 s18, s17, 0x7ffffe0
	s_lshl_b32 s17, s17, 1
	s_andn2_b32 s17, s17, 63
	s_sub_i32 s4, s4, s18
	v_or_b32_e32 v0, s17, v33
	s_lshl_b32 s18, s4, 5
	v_ashrrev_i32_e32 v1, 31, v0
	v_or_b32_e32 v6, 2, v0
	v_or_b32_e32 v8, 4, v0
	v_or_b32_e32 v10, 6, v0
	v_or_b32_e32 v12, 8, v0
	v_or_b32_e32 v14, 10, v0
	v_or_b32_e32 v16, 12, v0
	v_or_b32_e32 v18, 14, v0
	v_or_b32_e32 v20, 16, v0
	v_or_b32_e32 v22, 18, v0
	v_or_b32_e32 v24, 20, v0
	v_or_b32_e32 v26, 22, v0
	v_or_b32_e32 v28, 24, v0
	v_or_b32_e32 v30, 26, v0
	s_ashr_i32 s19, s18, 31
	v_lshlrev_b64 v[4:5], 12, v[0:1]
	v_ashrrev_i32_e32 v7, 31, v6
	v_ashrrev_i32_e32 v9, 31, v8
	v_ashrrev_i32_e32 v11, 31, v10
	v_ashrrev_i32_e32 v13, 31, v12
	v_ashrrev_i32_e32 v15, 31, v14
	v_ashrrev_i32_e32 v17, 31, v16
	v_ashrrev_i32_e32 v19, 31, v18
	v_ashrrev_i32_e32 v21, 31, v20
	v_ashrrev_i32_e32 v23, 31, v22
	v_ashrrev_i32_e32 v25, 31, v24
	v_ashrrev_i32_e32 v27, 31, v26
	v_ashrrev_i32_e32 v29, 31, v28
	v_ashrrev_i32_e32 v31, 31, v30
	v_or_b32_e32 v84, 28, v0
	v_or_b32_e32 v86, 30, v0
	v_or_b32_e32 v88, 32, v0
	v_or_b32_e32 v90, 34, v0
	v_or_b32_e32 v92, 36, v0
	v_or_b32_e32 v94, 38, v0
	v_or_b32_e32 v96, 40, v0
	v_or_b32_e32 v98, 42, v0
	v_or_b32_e32 v100, 44, v0
	v_or_b32_e32 v102, 46, v0
	v_or_b32_e32 v104, 48, v0
	v_or_b32_e32 v106, 50, v0
	v_or_b32_e32 v108, 52, v0
	v_or_b32_e32 v110, 54, v0
	v_or_b32_e32 v112, 56, v0
	v_or_b32_e32 v114, 58, v0
	v_or_b32_e32 v116, 60, v0
	v_or_b32_e32 v0, 62, v0
	v_lshl_add_u64 v[2:3], s[18:19], 2, v[34:35]
	v_lshlrev_b64 v[6:7], 12, v[6:7]
	v_lshlrev_b64 v[8:9], 12, v[8:9]
	v_lshlrev_b64 v[10:11], 12, v[10:11]
	v_lshlrev_b64 v[12:13], 12, v[12:13]
	v_lshlrev_b64 v[14:15], 12, v[14:15]
	v_lshlrev_b64 v[16:17], 12, v[16:17]
	v_lshlrev_b64 v[18:19], 12, v[18:19]
	v_lshlrev_b64 v[20:21], 12, v[20:21]
	v_lshlrev_b64 v[22:23], 12, v[22:23]
	v_lshlrev_b64 v[24:25], 12, v[24:25]
	v_lshlrev_b64 v[26:27], 12, v[26:27]
	v_lshlrev_b64 v[28:29], 12, v[28:29]
	v_lshlrev_b64 v[30:31], 12, v[30:31]
	v_ashrrev_i32_e32 v85, 31, v84
	v_ashrrev_i32_e32 v87, 31, v86
	v_ashrrev_i32_e32 v89, 31, v88
	v_ashrrev_i32_e32 v91, 31, v90
	v_ashrrev_i32_e32 v93, 31, v92
	v_ashrrev_i32_e32 v95, 31, v94
	v_ashrrev_i32_e32 v97, 31, v96
	v_ashrrev_i32_e32 v99, 31, v98
	v_ashrrev_i32_e32 v101, 31, v100
	v_ashrrev_i32_e32 v103, 31, v102
	v_ashrrev_i32_e32 v105, 31, v104
	v_ashrrev_i32_e32 v107, 31, v106
	v_ashrrev_i32_e32 v109, 31, v108
	v_ashrrev_i32_e32 v111, 31, v110
	v_ashrrev_i32_e32 v113, 31, v112
	v_ashrrev_i32_e32 v115, 31, v114
	v_ashrrev_i32_e32 v117, 31, v116
	v_ashrrev_i32_e32 v1, 31, v0
	v_lshl_add_u64 v[4:5], v[2:3], 0, v[4:5]
	v_lshl_add_u64 v[6:7], v[2:3], 0, v[6:7]
	v_lshl_add_u64 v[8:9], v[2:3], 0, v[8:9]
	v_lshl_add_u64 v[10:11], v[2:3], 0, v[10:11]
	v_lshl_add_u64 v[12:13], v[2:3], 0, v[12:13]
	v_lshl_add_u64 v[14:15], v[2:3], 0, v[14:15]
	v_lshl_add_u64 v[16:17], v[2:3], 0, v[16:17]
	v_lshl_add_u64 v[18:19], v[2:3], 0, v[18:19]
	v_lshl_add_u64 v[20:21], v[2:3], 0, v[20:21]
	v_lshl_add_u64 v[22:23], v[2:3], 0, v[22:23]
	v_lshl_add_u64 v[24:25], v[2:3], 0, v[24:25]
	v_lshl_add_u64 v[26:27], v[2:3], 0, v[26:27]
	v_lshl_add_u64 v[28:29], v[2:3], 0, v[28:29]
	v_lshl_add_u64 v[30:31], v[2:3], 0, v[30:31]
	v_lshlrev_b64 v[84:85], 12, v[84:85]
	v_lshlrev_b64 v[86:87], 12, v[86:87]
	v_lshlrev_b64 v[88:89], 12, v[88:89]
	v_lshlrev_b64 v[90:91], 12, v[90:91]
	v_lshlrev_b64 v[92:93], 12, v[92:93]
	v_lshlrev_b64 v[94:95], 12, v[94:95]
	v_lshlrev_b64 v[96:97], 12, v[96:97]
	v_lshlrev_b64 v[98:99], 12, v[98:99]
	v_lshlrev_b64 v[100:101], 12, v[100:101]
	v_lshlrev_b64 v[102:103], 12, v[102:103]
	v_lshlrev_b64 v[104:105], 12, v[104:105]
	v_lshlrev_b64 v[106:107], 12, v[106:107]
	v_lshlrev_b64 v[108:109], 12, v[108:109]
	v_lshlrev_b64 v[110:111], 12, v[110:111]
	v_lshlrev_b64 v[112:113], 12, v[112:113]
	v_lshlrev_b64 v[114:115], 12, v[114:115]
	v_lshlrev_b64 v[116:117], 12, v[116:117]
	v_lshlrev_b64 v[0:1], 12, v[0:1]
	v_lshl_add_u64 v[84:85], v[2:3], 0, v[84:85]
	v_lshl_add_u64 v[86:87], v[2:3], 0, v[86:87]
	v_lshl_add_u64 v[88:89], v[2:3], 0, v[88:89]
	v_lshl_add_u64 v[90:91], v[2:3], 0, v[90:91]
	v_lshl_add_u64 v[92:93], v[2:3], 0, v[92:93]
	v_lshl_add_u64 v[94:95], v[2:3], 0, v[94:95]
	v_lshl_add_u64 v[96:97], v[2:3], 0, v[96:97]
	v_lshl_add_u64 v[98:99], v[2:3], 0, v[98:99]
	v_lshl_add_u64 v[100:101], v[2:3], 0, v[100:101]
	v_lshl_add_u64 v[102:103], v[2:3], 0, v[102:103]
	v_lshl_add_u64 v[104:105], v[2:3], 0, v[104:105]
	v_lshl_add_u64 v[106:107], v[2:3], 0, v[106:107]
	v_lshl_add_u64 v[108:109], v[2:3], 0, v[108:109]
	v_lshl_add_u64 v[110:111], v[2:3], 0, v[110:111]
	v_lshl_add_u64 v[112:113], v[2:3], 0, v[112:113]
	v_lshl_add_u64 v[114:115], v[2:3], 0, v[114:115]
	v_lshl_add_u64 v[116:117], v[2:3], 0, v[116:117]
	v_lshl_add_u64 v[118:119], v[2:3], 0, v[0:1]
	global_load_dword v0, v[4:5], off
	global_load_dword v1, v[6:7], off
	global_load_dword v2, v[8:9], off
	global_load_dword v3, v[10:11], off
	s_nop 0
	global_load_dword v4, v[12:13], off
	global_load_dword v5, v[14:15], off
	global_load_dword v6, v[16:17], off
	global_load_dword v7, v[18:19], off
	global_load_dword v8, v[20:21], off
	global_load_dword v9, v[22:23], off
	global_load_dword v10, v[24:25], off
	global_load_dword v11, v[26:27], off
	global_load_dword v12, v[28:29], off
	global_load_dword v13, v[30:31], off
	global_load_dword v14, v[84:85], off
	global_load_dword v15, v[86:87], off
	global_load_dword v16, v[88:89], off
	global_load_dword v17, v[90:91], off
	global_load_dword v18, v[92:93], off
	global_load_dword v19, v[94:95], off
	global_load_dword v20, v[96:97], off
	global_load_dword v21, v[98:99], off
	global_load_dword v22, v[100:101], off
	global_load_dword v23, v[102:103], off
	global_load_dword v24, v[104:105], off
	global_load_dword v25, v[106:107], off
	global_load_dword v26, v[108:109], off
	global_load_dword v27, v[110:111], off
	global_load_dword v28, v[112:113], off
	global_load_dword v29, v[114:115], off
	global_load_dword v30, v[116:117], off
	global_load_dword v31, v[118:119], off
	s_branch .LwdB_b124
.Lwd_done:
	s_mov_b64 s[6:7], s[44:45]
